# row-sum check: compare issued before the bf16 packing, branch taken after it (hides the VALU-to-scalar latency of the test)
# speedup vs baseline: 1.0066x; 1.0005x over previous
.Lat_exp_a:
	v_exp_f32_e32 v130, v130
	v_exp_f32_e32 v131, v131
	v_exp_f32_e32 v132, v132
	v_add_f32_e32 v0, v130, v131
	v_exp_f32_e32 v133, v133
	v_add_f32_e32 v0, v0, v132
	v_exp_f32_e32 v134, v134
	v_add_f32_e32 v0, v0, v133
	v_exp_f32_e32 v135, v135
	v_add_f32_e32 v0, v0, v134
	v_exp_f32_e32 v136, v136
	v_add_f32_e32 v0, v0, v135
	v_exp_f32_e32 v137, v137
	v_add_f32_e32 v0, v0, v136
	v_exp_f32_e32 v138, v138
	v_add_f32_e32 v0, v0, v137
	v_exp_f32_e32 v139, v139
	v_add_f32_e32 v0, v0, v138
	v_exp_f32_e32 v140, v140
	v_add_f32_e32 v0, v0, v139
	v_exp_f32_e32 v141, v141
	v_add_f32_e32 v0, v0, v140
	v_exp_f32_e32 v142, v142
	v_add_f32_e32 v0, v0, v141
	v_exp_f32_e32 v143, v143
	v_add_f32_e32 v0, v0, v142
	v_exp_f32_e32 v144, v144
	v_add_f32_e32 v0, v0, v143
	v_exp_f32_e32 v145, v145
	v_add_f32_e32 v0, v0, v144
	v_exp_f32_e32 v146, v146
	v_exp_f32_e32 v147, v147
	v_exp_f32_e32 v148, v148
	v_add_f32_e32 v233, v146, v147
	v_exp_f32_e32 v149, v149
	v_add_f32_e32 v233, v233, v148
	v_exp_f32_e32 v150, v150
	v_add_f32_e32 v233, v233, v149
	v_exp_f32_e32 v151, v151
	v_add_f32_e32 v233, v233, v150
	v_exp_f32_e32 v152, v152
	v_add_f32_e32 v233, v233, v151
	v_exp_f32_e32 v153, v153
	v_add_f32_e32 v233, v233, v152
	v_exp_f32_e32 v154, v154
	v_add_f32_e32 v233, v233, v153
	v_exp_f32_e32 v155, v155
	v_add_f32_e32 v233, v233, v154
	v_exp_f32_e32 v156, v156
	v_add_f32_e32 v233, v233, v155
	v_exp_f32_e32 v157, v157
	v_add_f32_e32 v233, v233, v156
	v_exp_f32_e32 v158, v158
	v_add_f32_e32 v233, v233, v157
	v_exp_f32_e32 v159, v159
	v_add_f32_e32 v233, v233, v158
	v_exp_f32_e32 v160, v160
	v_add_f32_e32 v233, v233, v159
	v_exp_f32_e32 v161, v161
	v_add_f32_e32 v233, v233, v160
	v_add_f32_e32 v0, v0, v145
	v_add_f32_e32 v233, v233, v161
	v_max_f32_e32 v238, v0, v233
	v_cmp_ge_f32_e32 vcc, 0x43800000, v238
	v_cvt_pk_bf16_f32 v130, v130, v131
	v_cvt_pk_bf16_f32 v131, v132, v133
	v_cvt_pk_bf16_f32 v132, v134, v135
	v_cvt_pk_bf16_f32 v133, v136, v137
	v_cvt_pk_bf16_f32 v134, v138, v139
	v_cvt_pk_bf16_f32 v135, v140, v141
	v_cvt_pk_bf16_f32 v136, v142, v143
	v_cvt_pk_bf16_f32 v137, v144, v145
	v_cvt_pk_bf16_f32 v146, v146, v147
	v_cvt_pk_bf16_f32 v147, v148, v149
	v_cvt_pk_bf16_f32 v148, v150, v151
	v_cvt_pk_bf16_f32 v149, v152, v153
	v_cvt_pk_bf16_f32 v150, v154, v155
	v_cvt_pk_bf16_f32 v151, v156, v157
	v_cvt_pk_bf16_f32 v152, v158, v159
	v_cvt_pk_bf16_f32 v153, v160, v161
	s_cmp_eq_u64 vcc, exec
	s_cbranch_scc0 .Lat_redo_a
	v_add_f32_e32 v232, v232, v0
	v_add_f32_e32 v244, v244, v233
	s_waitcnt lgkmcnt(2)
	v_mfma_f32_16x16x32_bf16 v[114:117], v[162:165], v[130:133], v[114:117]
	v_mfma_f32_16x16x32_bf16 v[122:125], v[162:165], v[146:149], v[122:125]
	ds_read_b128 v[162:165], v242 offset:4096
	v_mfma_f32_16x16x32_bf16 v[114:117], v[166:169], v[134:137], v[114:117]
	v_mfma_f32_16x16x32_bf16 v[122:125], v[166:169], v[150:153], v[122:125]
	ds_read_b128 v[166:169], v243 offset:4096
	s_waitcnt lgkmcnt(2)
	v_mfma_f32_16x16x32_bf16 v[118:121], v[170:173], v[130:133], v[118:121]
	v_mfma_f32_16x16x32_bf16 v[126:129], v[170:173], v[146:149], v[126:129]
	ds_read_b128 v[170:173], v242 offset:6144
	v_mfma_f32_16x16x32_bf16 v[118:121], v[174:177], v[134:137], v[118:121]
	v_mfma_f32_16x16x32_bf16 v[126:129], v[174:177], v[150:153], v[126:129]
	ds_read_b128 v[174:177], v243 offset:6144
	s_waitcnt lgkmcnt(2)
	v_mfma_f32_16x16x32_bf16 v[98:101], v[162:165], v[130:133], v[98:101]
	v_mfma_f32_16x16x32_bf16 v[106:109], v[162:165], v[146:149], v[106:109]
	ds_read_b128 v[162:165], v242 offset:8192
	v_mfma_f32_16x16x32_bf16 v[98:101], v[166:169], v[134:137], v[98:101]
	v_mfma_f32_16x16x32_bf16 v[106:109], v[166:169], v[150:153], v[106:109]
	ds_read_b128 v[166:169], v243 offset:8192
	s_waitcnt lgkmcnt(2)
	v_mfma_f32_16x16x32_bf16 v[102:105], v[170:173], v[130:133], v[102:105]
	v_mfma_f32_16x16x32_bf16 v[110:113], v[170:173], v[146:149], v[110:113]
	ds_read_b128 v[170:173], v242 offset:10240
	v_mfma_f32_16x16x32_bf16 v[102:105], v[174:177], v[134:137], v[102:105]
	v_mfma_f32_16x16x32_bf16 v[110:113], v[174:177], v[150:153], v[110:113]
	ds_read_b128 v[174:177], v243 offset:10240
	s_waitcnt lgkmcnt(2)
	v_mfma_f32_16x16x32_bf16 v[82:85], v[162:165], v[130:133], v[82:85]
	v_mfma_f32_16x16x32_bf16 v[90:93], v[162:165], v[146:149], v[90:93]
	ds_read_b128 v[162:165], v242 offset:12288
	v_mfma_f32_16x16x32_bf16 v[82:85], v[166:169], v[134:137], v[82:85]
	v_mfma_f32_16x16x32_bf16 v[90:93], v[166:169], v[150:153], v[90:93]
	ds_read_b128 v[166:169], v243 offset:12288
	s_waitcnt lgkmcnt(2)
	v_mfma_f32_16x16x32_bf16 v[86:89], v[170:173], v[130:133], v[86:89]
	v_mfma_f32_16x16x32_bf16 v[94:97], v[170:173], v[146:149], v[94:97]
	ds_read_b128 v[170:173], v242 offset:14336
	v_mfma_f32_16x16x32_bf16 v[86:89], v[174:177], v[134:137], v[86:89]
	v_mfma_f32_16x16x32_bf16 v[94:97], v[174:177], v[150:153], v[94:97]
	ds_read_b128 v[174:177], v243 offset:14336
	s_waitcnt lgkmcnt(2)
	v_mfma_f32_16x16x32_bf16 v[66:69], v[162:165], v[130:133], v[66:69]
	v_mfma_f32_16x16x32_bf16 v[74:77], v[162:165], v[146:149], v[74:77]
	ds_read_b128 v[162:165], v242 offset:16384
	v_mfma_f32_16x16x32_bf16 v[66:69], v[166:169], v[134:137], v[66:69]
	v_mfma_f32_16x16x32_bf16 v[74:77], v[166:169], v[150:153], v[74:77]
	ds_read_b128 v[166:169], v243 offset:16384
	s_waitcnt lgkmcnt(2)
	v_mfma_f32_16x16x32_bf16 v[70:73], v[170:173], v[130:133], v[70:73]
	v_mfma_f32_16x16x32_bf16 v[78:81], v[170:173], v[146:149], v[78:81]
	ds_read_b128 v[170:173], v242 offset:18432
	v_mfma_f32_16x16x32_bf16 v[70:73], v[174:177], v[134:137], v[70:73]
	v_mfma_f32_16x16x32_bf16 v[78:81], v[174:177], v[150:153], v[78:81]
	ds_read_b128 v[174:177], v243 offset:18432
	s_waitcnt lgkmcnt(2)
	v_mfma_f32_16x16x32_bf16 v[50:53], v[162:165], v[130:133], v[50:53]
	v_mfma_f32_16x16x32_bf16 v[58:61], v[162:165], v[146:149], v[58:61]
	ds_read_b128 v[162:165], v242 offset:20480
	v_mfma_f32_16x16x32_bf16 v[50:53], v[166:169], v[134:137], v[50:53]
	v_mfma_f32_16x16x32_bf16 v[58:61], v[166:169], v[150:153], v[58:61]
	ds_read_b128 v[166:169], v243 offset:20480
	s_waitcnt lgkmcnt(2)
	v_mfma_f32_16x16x32_bf16 v[54:57], v[170:173], v[130:133], v[54:57]
	v_mfma_f32_16x16x32_bf16 v[62:65], v[170:173], v[146:149], v[62:65]
	ds_read_b128 v[170:173], v242 offset:22528
	v_mfma_f32_16x16x32_bf16 v[54:57], v[174:177], v[134:137], v[54:57]
	v_mfma_f32_16x16x32_bf16 v[62:65], v[174:177], v[150:153], v[62:65]
	ds_read_b128 v[174:177], v243 offset:22528
	s_waitcnt lgkmcnt(2)
	v_mfma_f32_16x16x32_bf16 v[34:37], v[162:165], v[130:133], v[34:37]
	v_mfma_f32_16x16x32_bf16 v[42:45], v[162:165], v[146:149], v[42:45]
	ds_read_b128 v[162:165], v242 offset:24576
	v_mfma_f32_16x16x32_bf16 v[34:37], v[166:169], v[134:137], v[34:37]
	v_mfma_f32_16x16x32_bf16 v[42:45], v[166:169], v[150:153], v[42:45]
	ds_read_b128 v[166:169], v243 offset:24576
	s_waitcnt lgkmcnt(2)
	v_mfma_f32_16x16x32_bf16 v[38:41], v[170:173], v[130:133], v[38:41]
	v_mfma_f32_16x16x32_bf16 v[46:49], v[170:173], v[146:149], v[46:49]
	ds_read_b128 v[170:173], v242 offset:26624
	v_mfma_f32_16x16x32_bf16 v[38:41], v[174:177], v[134:137], v[38:41]
	v_mfma_f32_16x16x32_bf16 v[46:49], v[174:177], v[150:153], v[46:49]
	ds_read_b128 v[174:177], v243 offset:26624
	s_waitcnt lgkmcnt(2)
	v_mfma_f32_16x16x32_bf16 v[18:21], v[162:165], v[130:133], v[18:21]
	v_mfma_f32_16x16x32_bf16 v[26:29], v[162:165], v[146:149], v[26:29]
	ds_read_b128 v[162:165], v242 offset:28672
	v_mfma_f32_16x16x32_bf16 v[18:21], v[166:169], v[134:137], v[18:21]
	v_mfma_f32_16x16x32_bf16 v[26:29], v[166:169], v[150:153], v[26:29]
	ds_read_b128 v[166:169], v243 offset:28672
	s_waitcnt lgkmcnt(2)
	v_mfma_f32_16x16x32_bf16 v[22:25], v[170:173], v[130:133], v[22:25]
	v_mfma_f32_16x16x32_bf16 v[30:33], v[170:173], v[146:149], v[30:33]
	ds_read_b128 v[170:173], v242 offset:30720
	v_mfma_f32_16x16x32_bf16 v[22:25], v[174:177], v[134:137], v[22:25]
	v_mfma_f32_16x16x32_bf16 v[30:33], v[174:177], v[150:153], v[30:33]
	ds_read_b128 v[174:177], v243 offset:30720
	s_waitcnt lgkmcnt(2)
	v_mfma_f32_16x16x32_bf16 v[2:5], v[162:165], v[130:133], v[2:5]
	v_mfma_f32_16x16x32_bf16 v[10:13], v[162:165], v[146:149], v[10:13]
	v_mfma_f32_16x16x32_bf16 v[2:5], v[166:169], v[134:137], v[2:5]
	v_mfma_f32_16x16x32_bf16 v[10:13], v[166:169], v[150:153], v[10:13]
	s_waitcnt lgkmcnt(0)
	v_mfma_f32_16x16x32_bf16 v[6:9], v[170:173], v[130:133], v[6:9]
	v_mfma_f32_16x16x32_bf16 v[14:17], v[170:173], v[146:149], v[14:17]
	v_mfma_f32_16x16x32_bf16 v[6:9], v[174:177], v[134:137], v[6:9]
	v_mfma_f32_16x16x32_bf16 v[14:17], v[174:177], v[150:153], v[14:17]
	s_branch .Lat_end_a

.Lat_exp_c:
	v_exp_f32_e32 v130, v130
	v_exp_f32_e32 v131, v131
	v_exp_f32_e32 v132, v132
	v_add_f32_e32 v0, v130, v131
	v_exp_f32_e32 v133, v133
	v_add_f32_e32 v0, v0, v132
	v_exp_f32_e32 v134, v134
	v_add_f32_e32 v0, v0, v133
	v_exp_f32_e32 v135, v135
	v_add_f32_e32 v0, v0, v134
	v_exp_f32_e32 v136, v136
	v_add_f32_e32 v0, v0, v135
	v_exp_f32_e32 v137, v137
	v_add_f32_e32 v0, v0, v136
	v_exp_f32_e32 v138, v138
	v_add_f32_e32 v0, v0, v137
	v_exp_f32_e32 v139, v139
	v_add_f32_e32 v0, v0, v138
	v_exp_f32_e32 v140, v140
	v_add_f32_e32 v0, v0, v139
	v_exp_f32_e32 v141, v141
	v_add_f32_e32 v0, v0, v140
	v_exp_f32_e32 v142, v142
	v_add_f32_e32 v0, v0, v141
	v_exp_f32_e32 v143, v143
	v_add_f32_e32 v0, v0, v142
	v_exp_f32_e32 v144, v144
	v_add_f32_e32 v0, v0, v143
	v_exp_f32_e32 v145, v145
	v_add_f32_e32 v0, v0, v144
	v_exp_f32_e32 v146, v146
	v_exp_f32_e32 v147, v147
	v_exp_f32_e32 v148, v148
	v_add_f32_e32 v233, v146, v147
	v_exp_f32_e32 v149, v149
	v_add_f32_e32 v233, v233, v148
	v_exp_f32_e32 v150, v150
	v_add_f32_e32 v233, v233, v149
	v_exp_f32_e32 v151, v151
	v_add_f32_e32 v233, v233, v150
	v_exp_f32_e32 v152, v152
	v_add_f32_e32 v233, v233, v151
	v_exp_f32_e32 v153, v153
	v_add_f32_e32 v233, v233, v152
	v_exp_f32_e32 v154, v154
	v_add_f32_e32 v233, v233, v153
	v_exp_f32_e32 v155, v155
	v_add_f32_e32 v233, v233, v154
	v_exp_f32_e32 v156, v156
	v_add_f32_e32 v233, v233, v155
	v_exp_f32_e32 v157, v157
	v_add_f32_e32 v233, v233, v156
	v_exp_f32_e32 v158, v158
	v_add_f32_e32 v233, v233, v157
	v_exp_f32_e32 v159, v159
	v_add_f32_e32 v233, v233, v158
	v_exp_f32_e32 v160, v160
	v_add_f32_e32 v233, v233, v159
	v_exp_f32_e32 v161, v161
	v_add_f32_e32 v233, v233, v160
	v_add_f32_e32 v0, v0, v145
	v_add_f32_e32 v233, v233, v161
	v_max_f32_e32 v238, v0, v233
	v_cmp_ge_f32_e32 vcc, 0x43800000, v238
	v_cvt_pk_bf16_f32 v130, v130, v131
	v_cvt_pk_bf16_f32 v131, v132, v133
	v_cvt_pk_bf16_f32 v132, v134, v135
	v_cvt_pk_bf16_f32 v133, v136, v137
	v_cvt_pk_bf16_f32 v134, v138, v139
	v_cvt_pk_bf16_f32 v135, v140, v141
	v_cvt_pk_bf16_f32 v136, v142, v143
	v_cvt_pk_bf16_f32 v137, v144, v145
	v_cvt_pk_bf16_f32 v146, v146, v147
	v_cvt_pk_bf16_f32 v147, v148, v149
	v_cvt_pk_bf16_f32 v148, v150, v151
	v_cvt_pk_bf16_f32 v149, v152, v153
	v_cvt_pk_bf16_f32 v150, v154, v155
	v_cvt_pk_bf16_f32 v151, v156, v157
	v_cvt_pk_bf16_f32 v152, v158, v159
	v_cvt_pk_bf16_f32 v153, v160, v161
	s_cmp_eq_u64 vcc, exec
	s_cbranch_scc0 .Lat_redo_c
	v_add_f32_e32 v232, v232, v0
	v_add_f32_e32 v244, v244, v233
	s_waitcnt lgkmcnt(2)
	v_mfma_f32_16x16x32_bf16 v[114:117], v[162:165], v[130:133], v[114:117]
	v_mfma_f32_16x16x32_bf16 v[122:125], v[162:165], v[146:149], v[122:125]
	ds_read_b128 v[162:165], v242 offset:36864
	v_mfma_f32_16x16x32_bf16 v[114:117], v[166:169], v[134:137], v[114:117]
	v_mfma_f32_16x16x32_bf16 v[122:125], v[166:169], v[150:153], v[122:125]
	ds_read_b128 v[166:169], v243 offset:36864
	s_waitcnt lgkmcnt(2)
	v_mfma_f32_16x16x32_bf16 v[118:121], v[170:173], v[130:133], v[118:121]
	v_mfma_f32_16x16x32_bf16 v[126:129], v[170:173], v[146:149], v[126:129]
	ds_read_b128 v[170:173], v242 offset:38912
	v_mfma_f32_16x16x32_bf16 v[118:121], v[174:177], v[134:137], v[118:121]
	v_mfma_f32_16x16x32_bf16 v[126:129], v[174:177], v[150:153], v[126:129]
	ds_read_b128 v[174:177], v243 offset:38912
	s_waitcnt lgkmcnt(2)
	v_mfma_f32_16x16x32_bf16 v[98:101], v[162:165], v[130:133], v[98:101]
	v_mfma_f32_16x16x32_bf16 v[106:109], v[162:165], v[146:149], v[106:109]
	ds_read_b128 v[162:165], v242 offset:40960
	v_mfma_f32_16x16x32_bf16 v[98:101], v[166:169], v[134:137], v[98:101]
	v_mfma_f32_16x16x32_bf16 v[106:109], v[166:169], v[150:153], v[106:109]
	ds_read_b128 v[166:169], v243 offset:40960
	s_waitcnt lgkmcnt(2)
	v_mfma_f32_16x16x32_bf16 v[102:105], v[170:173], v[130:133], v[102:105]
	v_mfma_f32_16x16x32_bf16 v[110:113], v[170:173], v[146:149], v[110:113]
	ds_read_b128 v[170:173], v242 offset:43008
	v_mfma_f32_16x16x32_bf16 v[102:105], v[174:177], v[134:137], v[102:105]
	v_mfma_f32_16x16x32_bf16 v[110:113], v[174:177], v[150:153], v[110:113]
	ds_read_b128 v[174:177], v243 offset:43008
	s_waitcnt lgkmcnt(2)
	v_mfma_f32_16x16x32_bf16 v[82:85], v[162:165], v[130:133], v[82:85]
	v_mfma_f32_16x16x32_bf16 v[90:93], v[162:165], v[146:149], v[90:93]
	ds_read_b128 v[162:165], v242 offset:45056
	v_mfma_f32_16x16x32_bf16 v[82:85], v[166:169], v[134:137], v[82:85]
	v_mfma_f32_16x16x32_bf16 v[90:93], v[166:169], v[150:153], v[90:93]
	ds_read_b128 v[166:169], v243 offset:45056
	s_waitcnt lgkmcnt(2)
	v_mfma_f32_16x16x32_bf16 v[86:89], v[170:173], v[130:133], v[86:89]
	v_mfma_f32_16x16x32_bf16 v[94:97], v[170:173], v[146:149], v[94:97]
	ds_read_b128 v[170:173], v242 offset:47104
	v_mfma_f32_16x16x32_bf16 v[86:89], v[174:177], v[134:137], v[86:89]
	v_mfma_f32_16x16x32_bf16 v[94:97], v[174:177], v[150:153], v[94:97]
	ds_read_b128 v[174:177], v243 offset:47104
	s_waitcnt lgkmcnt(2)
	v_mfma_f32_16x16x32_bf16 v[66:69], v[162:165], v[130:133], v[66:69]
	v_mfma_f32_16x16x32_bf16 v[74:77], v[162:165], v[146:149], v[74:77]
	ds_read_b128 v[162:165], v242 offset:49152
	v_mfma_f32_16x16x32_bf16 v[66:69], v[166:169], v[134:137], v[66:69]
	v_mfma_f32_16x16x32_bf16 v[74:77], v[166:169], v[150:153], v[74:77]
	ds_read_b128 v[166:169], v243 offset:49152
	s_waitcnt lgkmcnt(2)
	v_mfma_f32_16x16x32_bf16 v[70:73], v[170:173], v[130:133], v[70:73]
	v_mfma_f32_16x16x32_bf16 v[78:81], v[170:173], v[146:149], v[78:81]
	ds_read_b128 v[170:173], v242 offset:51200
	v_mfma_f32_16x16x32_bf16 v[70:73], v[174:177], v[134:137], v[70:73]
	v_mfma_f32_16x16x32_bf16 v[78:81], v[174:177], v[150:153], v[78:81]
	ds_read_b128 v[174:177], v243 offset:51200
	s_waitcnt lgkmcnt(2)
	v_mfma_f32_16x16x32_bf16 v[50:53], v[162:165], v[130:133], v[50:53]
	v_mfma_f32_16x16x32_bf16 v[58:61], v[162:165], v[146:149], v[58:61]
	ds_read_b128 v[162:165], v242 offset:53248
	v_mfma_f32_16x16x32_bf16 v[50:53], v[166:169], v[134:137], v[50:53]
	v_mfma_f32_16x16x32_bf16 v[58:61], v[166:169], v[150:153], v[58:61]
	ds_read_b128 v[166:169], v243 offset:53248
	s_waitcnt lgkmcnt(2)
	v_mfma_f32_16x16x32_bf16 v[54:57], v[170:173], v[130:133], v[54:57]
	v_mfma_f32_16x16x32_bf16 v[62:65], v[170:173], v[146:149], v[62:65]
	ds_read_b128 v[170:173], v242 offset:55296
	v_mfma_f32_16x16x32_bf16 v[54:57], v[174:177], v[134:137], v[54:57]
	v_mfma_f32_16x16x32_bf16 v[62:65], v[174:177], v[150:153], v[62:65]
	ds_read_b128 v[174:177], v243 offset:55296
	s_waitcnt lgkmcnt(2)
	v_mfma_f32_16x16x32_bf16 v[34:37], v[162:165], v[130:133], v[34:37]
	v_mfma_f32_16x16x32_bf16 v[42:45], v[162:165], v[146:149], v[42:45]
	ds_read_b128 v[162:165], v242 offset:57344
	v_mfma_f32_16x16x32_bf16 v[34:37], v[166:169], v[134:137], v[34:37]
	v_mfma_f32_16x16x32_bf16 v[42:45], v[166:169], v[150:153], v[42:45]
	ds_read_b128 v[166:169], v243 offset:57344
	s_waitcnt lgkmcnt(2)
	v_mfma_f32_16x16x32_bf16 v[38:41], v[170:173], v[130:133], v[38:41]
	v_mfma_f32_16x16x32_bf16 v[46:49], v[170:173], v[146:149], v[46:49]
	ds_read_b128 v[170:173], v242 offset:59392
	v_mfma_f32_16x16x32_bf16 v[38:41], v[174:177], v[134:137], v[38:41]
	v_mfma_f32_16x16x32_bf16 v[46:49], v[174:177], v[150:153], v[46:49]
	ds_read_b128 v[174:177], v243 offset:59392
	s_waitcnt lgkmcnt(2)
	v_mfma_f32_16x16x32_bf16 v[18:21], v[162:165], v[130:133], v[18:21]
	v_mfma_f32_16x16x32_bf16 v[26:29], v[162:165], v[146:149], v[26:29]
	ds_read_b128 v[162:165], v242 offset:61440
	v_mfma_f32_16x16x32_bf16 v[18:21], v[166:169], v[134:137], v[18:21]
	v_mfma_f32_16x16x32_bf16 v[26:29], v[166:169], v[150:153], v[26:29]
	ds_read_b128 v[166:169], v243 offset:61440
	s_waitcnt lgkmcnt(2)
	v_mfma_f32_16x16x32_bf16 v[22:25], v[170:173], v[130:133], v[22:25]
	v_mfma_f32_16x16x32_bf16 v[30:33], v[170:173], v[146:149], v[30:33]
	ds_read_b128 v[170:173], v242 offset:63488
	v_mfma_f32_16x16x32_bf16 v[22:25], v[174:177], v[134:137], v[22:25]
	v_mfma_f32_16x16x32_bf16 v[30:33], v[174:177], v[150:153], v[30:33]
	ds_read_b128 v[174:177], v243 offset:63488
	s_waitcnt lgkmcnt(2)
	v_mfma_f32_16x16x32_bf16 v[2:5], v[162:165], v[130:133], v[2:5]
	v_mfma_f32_16x16x32_bf16 v[10:13], v[162:165], v[146:149], v[10:13]
	v_mfma_f32_16x16x32_bf16 v[2:5], v[166:169], v[134:137], v[2:5]
	v_mfma_f32_16x16x32_bf16 v[10:13], v[166:169], v[150:153], v[10:13]
	s_waitcnt lgkmcnt(0)
	v_mfma_f32_16x16x32_bf16 v[6:9], v[170:173], v[130:133], v[6:9]
	v_mfma_f32_16x16x32_bf16 v[14:17], v[170:173], v[146:149], v[14:17]
	v_mfma_f32_16x16x32_bf16 v[6:9], v[174:177], v[134:137], v[6:9]
	v_mfma_f32_16x16x32_bf16 v[14:17], v[174:177], v[150:153], v[14:17]
	s_branch .Lat_end_c
